# rstd LDS cache (first tile of a GEMM phase computes the per-row rstd, later tiles re-read it): cached path without the dead row-sum chain, with a vmcnt(0) before its first store so the next tile's pre
# speedup vs baseline: 1.0061x; 1.0061x over previous
;     __device__ __forceinline__ void operator()(const f32x4 (&acc)[2][2][4][2], const Unit& u, int wr, int wc, int fr, int fq) const {
;         const int row0 = u.pm * BM + wr * 64 + fr, col0 = u.pn * BM + wc * 32 + 8 * fq;
;         float rsv[2][4];
; #pragma unroll
;         for (int ai = 0; ai < 2; ++ai) {
; #pragma unroll
;             for (int m = 0; m < 4; ++m) rsv[ai][m] = row_rstd16_coop(ssq, row0 + ai * HALF + m * 16, fq, 1.0f / 1024.0f);
;         }
; #pragma unroll
;         for (int ai = 0; ai < 2; ++ai)
; #pragma unroll
;             for (int m = 0; m < 4; ++m) {
;                 const int row = row0 + ai * HALF + m * 16;
;                 const float rs = rsv[ai][m];
;                 bf16_t* rowp = H + (size_t)row * ldh + (col0 >> 1);
; #pragma unroll
;                 for (int bj = 0; bj < 2; ++bj) {
;                     const f32x4 v0 = acc[ai][bj][m][0] * rs, v1 = acc[ai][bj][m][1] * rs;
.Lmy_rs_cached_0:
	v_lshlrev_b32_e32 v212, 2, v1
	v_add_u32_e32 v212, 0x21000, v212
	ds_read_b32 v182, v212
	ds_read_b32 v186, v212 offset:64
	ds_read_b32 v190, v212 offset:128
	ds_read_b32 v194, v212 offset:192
	ds_read_b32 v198, v212 offset:512
	ds_read_b32 v202, v212 offset:576
	ds_read_b32 v206, v212 offset:640
	ds_read_b32 v210, v212 offset:704
	s_waitcnt lgkmcnt(0)
	v_lshl_add_u32 v156, s58, 8, v1
	v_ashrrev_i32_e32 v157, 31, v156
	v_lshlrev_b64 v[130:131], 6, v[156:157]
	v_lshl_add_u64 v[130:131], v[142:143], 0, v[130:131]
	v_or_b32_e32 v174, 16, v156
	v_ashrrev_i32_e32 v175, 31, v174
	v_or_b32_e32 v170, 32, v156
	v_ashrrev_i32_e32 v171, 31, v170
	v_or_b32_e32 v166, 48, v156
	v_ashrrev_i32_e32 v167, 31, v166
	v_add_u32_e32 v162, 0x80, v156
	v_ashrrev_i32_e32 v163, 31, v162
	v_add_u32_e32 v158, 0x90, v156
	v_ashrrev_i32_e32 v159, 31, v158
	v_add_u32_e32 v152, 0xa0, v156
	v_ashrrev_i32_e32 v153, 31, v152
	s_and_b64 vcc, exec, s[4:5]
	v_mov_b32_e32 v148, v131
	v_mov_b32_e32 v149, v132
	s_nop 0
	s_nop 1
	s_waitcnt lgkmcnt(0)
	s_nop 1
	s_waitcnt lgkmcnt(0)
	v_mov_b32_e32 v176, v182
	s_nop 1
	v_pk_mul_f32 v[122:123], v[122:123], v[176:177] op_sel_hi:[1,0]
	v_pk_mul_f32 v[124:125], v[124:125], v[176:177] op_sel_hi:[1,0]
	v_pk_mul_f32 v[126:127], v[126:127], v[176:177] op_sel_hi:[1,0]
	v_pk_mul_f32 v[128:129], v[128:129], v[176:177] op_sel_hi:[1,0]
	v_pk_mul_f32 v[118:119], v[118:119], v[176:177] op_sel_hi:[1,0]
	v_pk_mul_f32 v[120:121], v[120:121], v[176:177] op_sel_hi:[1,0]
	v_pk_mul_f32 v[114:115], v[114:115], v[176:177] op_sel_hi:[1,0]
	v_pk_mul_f32 v[116:117], v[116:117], v[176:177] op_sel_hi:[1,0]
	s_nop 0
	s_nop 1
	s_waitcnt lgkmcnt(0)
	s_nop 1
	s_waitcnt lgkmcnt(0)
	v_mov_b32_e32 v172, v186
	s_nop 1
	v_pk_mul_f32 v[110:111], v[110:111], v[172:173] op_sel_hi:[1,0]
	v_pk_mul_f32 v[112:113], v[112:113], v[172:173] op_sel_hi:[1,0]
	v_pk_mul_f32 v[106:107], v[106:107], v[172:173] op_sel_hi:[1,0]
	v_pk_mul_f32 v[108:109], v[108:109], v[172:173] op_sel_hi:[1,0]
	v_pk_mul_f32 v[102:103], v[102:103], v[172:173] op_sel_hi:[1,0]
	v_pk_mul_f32 v[104:105], v[104:105], v[172:173] op_sel_hi:[1,0]
	v_pk_mul_f32 v[98:99], v[98:99], v[172:173] op_sel_hi:[1,0]
	v_pk_mul_f32 v[100:101], v[100:101], v[172:173] op_sel_hi:[1,0]
	s_nop 0
	s_nop 1
	s_waitcnt lgkmcnt(0)
	s_nop 1
	s_waitcnt lgkmcnt(0)
	v_mov_b32_e32 v168, v190
	s_nop 1
	v_pk_mul_f32 v[94:95], v[94:95], v[168:169] op_sel_hi:[1,0]
	v_pk_mul_f32 v[96:97], v[96:97], v[168:169] op_sel_hi:[1,0]
	v_pk_mul_f32 v[90:91], v[90:91], v[168:169] op_sel_hi:[1,0]
	v_pk_mul_f32 v[92:93], v[92:93], v[168:169] op_sel_hi:[1,0]
	v_pk_mul_f32 v[86:87], v[86:87], v[168:169] op_sel_hi:[1,0]
	v_pk_mul_f32 v[88:89], v[88:89], v[168:169] op_sel_hi:[1,0]
	v_pk_mul_f32 v[82:83], v[82:83], v[168:169] op_sel_hi:[1,0]
	v_pk_mul_f32 v[84:85], v[84:85], v[168:169] op_sel_hi:[1,0]
	s_nop 0
	s_nop 1
	s_waitcnt lgkmcnt(0)
	s_nop 1
	s_waitcnt lgkmcnt(0)
	v_mov_b32_e32 v164, v194
	s_nop 1
	v_pk_mul_f32 v[78:79], v[78:79], v[164:165] op_sel_hi:[1,0]
	v_pk_mul_f32 v[80:81], v[80:81], v[164:165] op_sel_hi:[1,0]
	v_pk_mul_f32 v[74:75], v[74:75], v[164:165] op_sel_hi:[1,0]
	v_pk_mul_f32 v[76:77], v[76:77], v[164:165] op_sel_hi:[1,0]
	v_pk_mul_f32 v[70:71], v[70:71], v[164:165] op_sel_hi:[1,0]
	v_pk_mul_f32 v[72:73], v[72:73], v[164:165] op_sel_hi:[1,0]
	v_pk_mul_f32 v[66:67], v[66:67], v[164:165] op_sel_hi:[1,0]
	v_pk_mul_f32 v[68:69], v[68:69], v[164:165] op_sel_hi:[1,0]
	s_nop 0
	s_nop 1
	s_waitcnt lgkmcnt(0)
	s_nop 1
	s_waitcnt lgkmcnt(0)
	v_mov_b32_e32 v160, v198
	s_nop 1
	v_pk_mul_f32 v[62:63], v[62:63], v[160:161] op_sel_hi:[1,0]
	v_pk_mul_f32 v[64:65], v[64:65], v[160:161] op_sel_hi:[1,0]
	v_pk_mul_f32 v[58:59], v[58:59], v[160:161] op_sel_hi:[1,0]
	v_pk_mul_f32 v[60:61], v[60:61], v[160:161] op_sel_hi:[1,0]
	v_pk_mul_f32 v[54:55], v[54:55], v[160:161] op_sel_hi:[1,0]
	v_pk_mul_f32 v[56:57], v[56:57], v[160:161] op_sel_hi:[1,0]
	v_pk_mul_f32 v[50:51], v[50:51], v[160:161] op_sel_hi:[1,0]
	v_pk_mul_f32 v[52:53], v[52:53], v[160:161] op_sel_hi:[1,0]
	s_nop 0
	s_nop 1
	s_waitcnt lgkmcnt(0)
	s_nop 1
	s_waitcnt lgkmcnt(0)
	v_mov_b32_e32 v154, v202
	s_nop 1
	v_pk_mul_f32 v[46:47], v[46:47], v[154:155] op_sel_hi:[1,0]
	v_pk_mul_f32 v[48:49], v[48:49], v[154:155] op_sel_hi:[1,0]
	v_pk_mul_f32 v[42:43], v[42:43], v[154:155] op_sel_hi:[1,0]
	v_pk_mul_f32 v[44:45], v[44:45], v[154:155] op_sel_hi:[1,0]
	v_pk_mul_f32 v[38:39], v[38:39], v[154:155] op_sel_hi:[1,0]
	v_pk_mul_f32 v[40:41], v[40:41], v[154:155] op_sel_hi:[1,0]
	v_pk_mul_f32 v[34:35], v[34:35], v[154:155] op_sel_hi:[1,0]
	v_pk_mul_f32 v[36:37], v[36:37], v[154:155] op_sel_hi:[1,0]
	v_add_u32_e32 v148, 0xb0, v156
	s_nop 1
	v_ashrrev_i32_e32 v149, 31, v148
	s_waitcnt lgkmcnt(0)
	s_nop 1
	s_waitcnt lgkmcnt(0)
	v_mov_b32_e32 v150, v206
	s_nop 1
	v_pk_mul_f32 v[30:31], v[30:31], v[150:151] op_sel_hi:[1,0]
	v_pk_mul_f32 v[32:33], v[32:33], v[150:151] op_sel_hi:[1,0]
	v_pk_mul_f32 v[26:27], v[26:27], v[150:151] op_sel_hi:[1,0]
	v_pk_mul_f32 v[28:29], v[28:29], v[150:151] op_sel_hi:[1,0]
	v_pk_mul_f32 v[22:23], v[22:23], v[150:151] op_sel_hi:[1,0]
	v_pk_mul_f32 v[24:25], v[24:25], v[150:151] op_sel_hi:[1,0]
	v_pk_mul_f32 v[18:19], v[18:19], v[150:151] op_sel_hi:[1,0]
	v_pk_mul_f32 v[20:21], v[20:21], v[150:151] op_sel_hi:[1,0]
	v_mov_b64_e32 v[132:133], s[22:23]
	s_nop 1
	v_mad_i64_i32 v[180:181], s[30:31], v156, s96, v[132:133]
	s_waitcnt lgkmcnt(0)
	s_nop 1
	s_waitcnt lgkmcnt(0)
	v_lshl_or_b32 v131, s57, 8, v155
	v_ashrrev_i32_e32 v178, 1, v131
	v_mul_f32_e32 v131, 0xbfb8aa3b, v122
	v_exp_f32_e32 v131, v131
	v_ashrrev_i32_e32 v179, 31, v178
	v_lshlrev_b64 v[156:157], 1, v[178:179]
	v_lshl_add_u64 v[178:179], v[180:181], 0, v[156:157]
	v_add_f32_e32 v131, 1.0, v131
	v_rcp_f32_e32 v131, v131
	v_mov_b32_e32 v130, v210
; __device__ __forceinline__ unsigned cvt_pk_bf16(float lo, float hi) { unsigned r; asm volatile("v_cvt_pk_bf16_f32 %0, %1, %2" : "=v"(r) : "v"(lo), "v"(hi)); return r; }
;     __device__ __forceinline__ static float sg(float g, float uu) { return g * __builtin_amdgcn_rcpf(1.0f + __builtin_amdgcn_exp2f(-1.4426950408889634f * g)) * uu; }
;     __device__ __forceinline__ void operator()(const f32x4 (&acc)[2][2][4][2], const Unit& u, int wr, int wc, int fr, int fq) const {
;         const int row0 = u.pm * BM + wr * 64 + fr, col0 = u.pn * BM + wc * 32 + 8 * fq;
;         float rsv[2][4];
; #pragma unroll
;         for (int ai = 0; ai < 2; ++ai) {
; #pragma unroll
;             for (int m = 0; m < 4; ++m) rsv[ai][m] = row_rstd16_coop(ssq, row0 + ai * HALF + m * 16, fq, 1.0f / 1024.0f);
;         }
; #pragma unroll
;         for (int ai = 0; ai < 2; ++ai)
; #pragma unroll
;             for (int m = 0; m < 4; ++m) {
;                 const int row = row0 + ai * HALF + m * 16;
;                 const float rs = rsv[ai][m];
;                 bf16_t* rowp = H + (size_t)row * ldh + (col0 >> 1);
; #pragma unroll
;                 for (int bj = 0; bj < 2; ++bj) {
;                     const f32x4 v0 = acc[ai][bj][m][0] * rs, v1 = acc[ai][bj][m][1] * rs;
;                     u32x2 w; w.x = cvt_pk_bf16(sg(v0[0], v0[1]), sg(v0[2], v0[3])); w.y = cvt_pk_bf16(sg(v1[0], v1[1]), sg(v1[2], v1[3]));
;                     *(u32x2*)(rowp + bj * (HALF / 2)) = w;
;                 }
;             }
.Lmy_rs_join_0:
	v_mul_f32_e32 v122, v122, v131
	v_mul_f32_e32 v122, v123, v122
	v_mul_f32_e32 v123, 0xbfb8aa3b, v124
	v_exp_f32_e32 v123, v123
	v_pk_mul_f32 v[14:15], v[14:15], v[130:131] op_sel_hi:[1,0]
	v_pk_mul_f32 v[16:17], v[16:17], v[130:131] op_sel_hi:[1,0]
	v_pk_mul_f32 v[10:11], v[10:11], v[130:131] op_sel_hi:[1,0]
	v_add_f32_e32 v123, 1.0, v123
	v_rcp_f32_e32 v123, v123
	v_pk_mul_f32 v[12:13], v[12:13], v[130:131] op_sel_hi:[1,0]
	v_pk_mul_f32 v[6:7], v[6:7], v[130:131] op_sel_hi:[1,0]
	v_pk_mul_f32 v[8:9], v[8:9], v[130:131] op_sel_hi:[1,0]
	v_mul_f32_e32 v123, v124, v123
	v_mul_f32_e32 v123, v125, v123
	v_cvt_pk_bf16_f32 v122, v122, v123
	v_mul_f32_e32 v123, 0xbfb8aa3b, v126
	v_exp_f32_e32 v123, v123
	v_mul_f32_e32 v124, 0xbfb8aa3b, v128
	v_exp_f32_e32 v124, v124
	v_pk_mul_f32 v[2:3], v[2:3], v[130:131] op_sel_hi:[1,0]
	v_add_f32_e32 v123, 1.0, v123
	v_rcp_f32_e32 v123, v123
	v_add_f32_e32 v124, 1.0, v124
	v_rcp_f32_e32 v124, v124
	v_pk_mul_f32 v[4:5], v[4:5], v[130:131] op_sel_hi:[1,0]
	v_mul_f32_e32 v123, v126, v123
	v_mul_f32_e32 v123, v127, v123
	v_mul_f32_e32 v124, v128, v124
	v_mul_f32_e32 v124, v129, v124
	v_cvt_pk_bf16_f32 v123, v123, v124
	s_waitcnt vmcnt(0)
	global_store_dwordx2 v[178:179], v[122:123], off
	v_mul_f32_e32 v122, 0xbfb8aa3b, v118
	v_exp_f32_e32 v122, v122
	s_nop 0
	v_add_f32_e32 v122, 1.0, v122
	v_rcp_f32_e32 v122, v122
	s_nop 0
	v_mul_f32_e32 v118, v118, v122
	v_mul_f32_e32 v118, v119, v118
	v_mul_f32_e32 v119, 0xbfb8aa3b, v120
	v_exp_f32_e32 v119, v119
	s_nop 0
	v_add_f32_e32 v119, 1.0, v119
	v_rcp_f32_e32 v119, v119
	s_nop 0
	v_mul_f32_e32 v119, v120, v119
	v_mul_f32_e32 v119, v121, v119
	v_cvt_pk_bf16_f32 v118, v118, v119
	v_mul_f32_e32 v119, 0xbfb8aa3b, v114
	v_exp_f32_e32 v119, v119
	s_nop 0
	v_add_f32_e32 v119, 1.0, v119
	v_rcp_f32_e32 v119, v119
	s_nop 0
	v_mul_f32_e32 v114, v114, v119
	v_mul_f32_e32 v114, v115, v114
	v_mul_f32_e32 v115, 0xbfb8aa3b, v116
	v_exp_f32_e32 v115, v115
	s_nop 0
	v_add_f32_e32 v115, 1.0, v115
	v_rcp_f32_e32 v115, v115
	s_nop 0
	v_mul_f32_e32 v115, v116, v115
	v_mul_f32_e32 v116, 0xbfb8aa3b, v110
	v_exp_f32_e32 v116, v116
	v_mul_f32_e32 v115, v117, v115
	v_cvt_pk_bf16_f32 v119, v114, v115
	global_store_dwordx2 v[178:179], v[118:119], off offset:128
	v_add_f32_e32 v116, 1.0, v116
	v_rcp_f32_e32 v116, v116
	v_mad_i64_i32 v[114:115], s[30:31], v174, s96, v[132:133]
	v_lshl_add_u64 v[114:115], v[114:115], 0, v[156:157]
	v_mul_f32_e32 v110, v110, v116
	v_mul_f32_e32 v110, v111, v110
	v_mul_f32_e32 v111, 0xbfb8aa3b, v112
	v_exp_f32_e32 v111, v111
	s_nop 0
	v_add_f32_e32 v111, 1.0, v111
	v_rcp_f32_e32 v111, v111
	s_nop 0
	v_mul_f32_e32 v111, v112, v111
	v_mul_f32_e32 v111, v113, v111
	v_cvt_pk_bf16_f32 v110, v110, v111
	v_mul_f32_e32 v111, 0xbfb8aa3b, v106
	v_exp_f32_e32 v111, v111
	s_nop 0
	v_add_f32_e32 v111, 1.0, v111
	v_rcp_f32_e32 v111, v111
	s_nop 0
	v_mul_f32_e32 v106, v106, v111
	v_mul_f32_e32 v106, v107, v106
	v_mul_f32_e32 v107, 0xbfb8aa3b, v108
	v_exp_f32_e32 v107, v107
	s_nop 0
	v_add_f32_e32 v107, 1.0, v107
	v_rcp_f32_e32 v107, v107
	s_nop 0
	v_mul_f32_e32 v107, v108, v107
	v_mul_f32_e32 v107, v109, v107
	v_cvt_pk_bf16_f32 v111, v106, v107
	v_mul_f32_e32 v106, 0xbfb8aa3b, v102
	v_exp_f32_e32 v106, v106
	global_store_dwordx2 v[114:115], v[110:111], off
	v_add_f32_e32 v106, 1.0, v106
	v_rcp_f32_e32 v106, v106
	s_nop 0
	v_mul_f32_e32 v102, v102, v106
	v_mul_f32_e32 v102, v103, v102
	v_mul_f32_e32 v103, 0xbfb8aa3b, v104
	v_exp_f32_e32 v103, v103
	s_nop 0
	v_add_f32_e32 v103, 1.0, v103
	v_rcp_f32_e32 v103, v103
	s_nop 0
	v_mul_f32_e32 v103, v104, v103
	v_mul_f32_e32 v103, v105, v103
	v_cvt_pk_bf16_f32 v102, v102, v103
	v_mul_f32_e32 v103, 0xbfb8aa3b, v98
	v_exp_f32_e32 v103, v103
	s_nop 0
	v_add_f32_e32 v103, 1.0, v103
	v_rcp_f32_e32 v103, v103
	s_nop 0
	v_mul_f32_e32 v98, v98, v103
	v_mul_f32_e32 v98, v99, v98
	v_mul_f32_e32 v99, 0xbfb8aa3b, v100
	v_exp_f32_e32 v99, v99
	s_nop 0
	v_add_f32_e32 v99, 1.0, v99
	v_rcp_f32_e32 v99, v99
	s_nop 0
	v_mul_f32_e32 v99, v100, v99
	v_mul_f32_e32 v100, 0xbfb8aa3b, v94
	v_exp_f32_e32 v100, v100
	v_mul_f32_e32 v99, v101, v99
	v_cvt_pk_bf16_f32 v103, v98, v99
	global_store_dwordx2 v[114:115], v[102:103], off offset:128
	v_add_f32_e32 v100, 1.0, v100
	v_rcp_f32_e32 v100, v100
	v_mad_i64_i32 v[98:99], s[30:31], v170, s96, v[132:133]
	v_lshl_add_u64 v[98:99], v[98:99], 0, v[156:157]
	v_mul_f32_e32 v94, v94, v100
	v_mul_f32_e32 v94, v95, v94
	v_mul_f32_e32 v95, 0xbfb8aa3b, v96
	v_exp_f32_e32 v95, v95
	s_nop 0
	v_add_f32_e32 v95, 1.0, v95
	v_rcp_f32_e32 v95, v95
	s_nop 0
	v_mul_f32_e32 v95, v96, v95
	v_mul_f32_e32 v95, v97, v95
	v_cvt_pk_bf16_f32 v94, v94, v95
	v_mul_f32_e32 v95, 0xbfb8aa3b, v90
	v_exp_f32_e32 v95, v95
	s_nop 0
	v_add_f32_e32 v95, 1.0, v95
	v_rcp_f32_e32 v95, v95
	s_nop 0
	v_mul_f32_e32 v90, v90, v95
	v_mul_f32_e32 v90, v91, v90
	v_mul_f32_e32 v91, 0xbfb8aa3b, v92
	v_exp_f32_e32 v91, v91
	s_nop 0
	v_add_f32_e32 v91, 1.0, v91
	v_rcp_f32_e32 v91, v91
	s_nop 0
	v_mul_f32_e32 v91, v92, v91
	v_mul_f32_e32 v91, v93, v91
	v_cvt_pk_bf16_f32 v95, v90, v91
	v_mul_f32_e32 v90, 0xbfb8aa3b, v86
	v_exp_f32_e32 v90, v90
	global_store_dwordx2 v[98:99], v[94:95], off
	v_add_f32_e32 v90, 1.0, v90
	v_rcp_f32_e32 v90, v90
	s_nop 0
	v_mul_f32_e32 v86, v86, v90
	v_mul_f32_e32 v86, v87, v86
	v_mul_f32_e32 v87, 0xbfb8aa3b, v88
	v_exp_f32_e32 v87, v87
	s_nop 0
	v_add_f32_e32 v87, 1.0, v87
	v_rcp_f32_e32 v87, v87
	s_nop 0
	v_mul_f32_e32 v87, v88, v87
	v_mul_f32_e32 v87, v89, v87
	v_cvt_pk_bf16_f32 v86, v86, v87
	v_mul_f32_e32 v87, 0xbfb8aa3b, v82
	v_exp_f32_e32 v87, v87
	s_nop 0
	v_add_f32_e32 v87, 1.0, v87
	v_rcp_f32_e32 v87, v87
	s_nop 0
; __device__ __forceinline__ unsigned cvt_pk_bf16(float lo, float hi) { unsigned r; asm volatile("v_cvt_pk_bf16_f32 %0, %1, %2" : "=v"(r) : "v"(lo), "v"(hi)); return r; }
;     __device__ __forceinline__ static float sg(float g, float uu) { return g * __builtin_amdgcn_rcpf(1.0f + __builtin_amdgcn_exp2f(-1.4426950408889634f * g)) * uu; }
;     __device__ __forceinline__ void operator()(const f32x4 (&acc)[2][2][4][2], const Unit& u, int wr, int wc, int fr, int fq) const {
;     ...
;         for (int ai = 0; ai < 2; ++ai)
; #pragma unroll
;             for (int m = 0; m < 4; ++m) {
;                 const int row = row0 + ai * HALF + m * 16;
;                 const float rs = rsv[ai][m];
;                 bf16_t* rowp = H + (size_t)row * ldh + (col0 >> 1);
; #pragma unroll
;                 for (int bj = 0; bj < 2; ++bj) {
;                     const f32x4 v0 = acc[ai][bj][m][0] * rs, v1 = acc[ai][bj][m][1] * rs;
;                     u32x2 w; w.x = cvt_pk_bf16(sg(v0[0], v0[1]), sg(v0[2], v0[3])); w.y = cvt_pk_bf16(sg(v1[0], v1[1]), sg(v1[2], v1[3]));
;                     *(u32x2*)(rowp + bj * (HALF / 2)) = w;
;                 }
;             }
	v_mul_f32_e32 v82, v82, v87
	v_mul_f32_e32 v82, v83, v82
	v_mul_f32_e32 v83, 0xbfb8aa3b, v84
	v_exp_f32_e32 v83, v83
	s_nop 0
	v_add_f32_e32 v83, 1.0, v83
	v_rcp_f32_e32 v83, v83
	s_nop 0
	v_mul_f32_e32 v83, v84, v83
	v_mul_f32_e32 v84, 0xbfb8aa3b, v78
	v_exp_f32_e32 v84, v84
	v_mul_f32_e32 v83, v85, v83
	v_cvt_pk_bf16_f32 v87, v82, v83
	global_store_dwordx2 v[98:99], v[86:87], off offset:128
	v_add_f32_e32 v84, 1.0, v84
	v_rcp_f32_e32 v84, v84
	v_mad_i64_i32 v[82:83], s[30:31], v166, s96, v[132:133]
	v_lshl_add_u64 v[82:83], v[82:83], 0, v[156:157]
	v_mul_f32_e32 v78, v78, v84
	v_mul_f32_e32 v78, v79, v78
	v_mul_f32_e32 v79, 0xbfb8aa3b, v80
	v_exp_f32_e32 v79, v79
	s_nop 0
	v_add_f32_e32 v79, 1.0, v79
	v_rcp_f32_e32 v79, v79
	s_nop 0
	v_mul_f32_e32 v79, v80, v79
	v_mul_f32_e32 v79, v81, v79
	v_cvt_pk_bf16_f32 v78, v78, v79
	v_mul_f32_e32 v79, 0xbfb8aa3b, v74
	v_exp_f32_e32 v79, v79
	s_nop 0
	v_add_f32_e32 v79, 1.0, v79
	v_rcp_f32_e32 v79, v79
	s_nop 0
	v_mul_f32_e32 v74, v74, v79
	v_mul_f32_e32 v74, v75, v74
	v_mul_f32_e32 v75, 0xbfb8aa3b, v76
	v_exp_f32_e32 v75, v75
	s_nop 0
	v_add_f32_e32 v75, 1.0, v75
	v_rcp_f32_e32 v75, v75
	s_nop 0
	v_mul_f32_e32 v75, v76, v75
	v_mul_f32_e32 v75, v77, v75
	v_cvt_pk_bf16_f32 v79, v74, v75
	v_mul_f32_e32 v74, 0xbfb8aa3b, v70
	v_exp_f32_e32 v74, v74
	global_store_dwordx2 v[82:83], v[78:79], off
	v_add_f32_e32 v74, 1.0, v74
	v_rcp_f32_e32 v74, v74
	s_nop 0
	v_mul_f32_e32 v70, v70, v74
	v_mul_f32_e32 v70, v71, v70
	v_mul_f32_e32 v71, 0xbfb8aa3b, v72
	v_exp_f32_e32 v71, v71
	s_nop 0
	v_add_f32_e32 v71, 1.0, v71
	v_rcp_f32_e32 v71, v71
	s_nop 0
	v_mul_f32_e32 v71, v72, v71
	v_mul_f32_e32 v71, v73, v71
	v_cvt_pk_bf16_f32 v70, v70, v71
	v_mul_f32_e32 v71, 0xbfb8aa3b, v66
	v_exp_f32_e32 v71, v71
	s_nop 0
	v_add_f32_e32 v71, 1.0, v71
	v_rcp_f32_e32 v71, v71
	s_nop 0
	v_mul_f32_e32 v66, v66, v71
	v_mul_f32_e32 v66, v67, v66
	v_mul_f32_e32 v67, 0xbfb8aa3b, v68
	v_exp_f32_e32 v67, v67
	s_nop 0
	v_add_f32_e32 v67, 1.0, v67
	v_rcp_f32_e32 v67, v67
	s_nop 0
	v_mul_f32_e32 v67, v68, v67
	v_mul_f32_e32 v68, 0xbfb8aa3b, v62
	v_exp_f32_e32 v68, v68
	v_mul_f32_e32 v67, v69, v67
	v_cvt_pk_bf16_f32 v71, v66, v67
	global_store_dwordx2 v[82:83], v[70:71], off offset:128
	v_add_f32_e32 v68, 1.0, v68
	v_rcp_f32_e32 v68, v68
	v_mad_i64_i32 v[66:67], s[30:31], v162, s96, v[132:133]
	v_lshl_add_u64 v[66:67], v[66:67], 0, v[156:157]
	v_mul_f32_e32 v62, v62, v68
	v_mul_f32_e32 v62, v63, v62
	v_mul_f32_e32 v63, 0xbfb8aa3b, v64
	v_exp_f32_e32 v63, v63
	s_nop 0
	v_add_f32_e32 v63, 1.0, v63
	v_rcp_f32_e32 v63, v63
	s_nop 0
	v_mul_f32_e32 v63, v64, v63
	v_mul_f32_e32 v63, v65, v63
	v_cvt_pk_bf16_f32 v62, v62, v63
	v_mul_f32_e32 v63, 0xbfb8aa3b, v58
	v_exp_f32_e32 v63, v63
	s_nop 0
	v_add_f32_e32 v63, 1.0, v63
	v_rcp_f32_e32 v63, v63
	s_nop 0
	v_mul_f32_e32 v58, v58, v63
	v_mul_f32_e32 v58, v59, v58
	v_mul_f32_e32 v59, 0xbfb8aa3b, v60
	v_exp_f32_e32 v59, v59
	s_nop 0
	v_add_f32_e32 v59, 1.0, v59
	v_rcp_f32_e32 v59, v59
	s_nop 0
	v_mul_f32_e32 v59, v60, v59
	v_mul_f32_e32 v59, v61, v59
	v_cvt_pk_bf16_f32 v63, v58, v59
	v_mul_f32_e32 v58, 0xbfb8aa3b, v54
	v_exp_f32_e32 v58, v58
	global_store_dwordx2 v[66:67], v[62:63], off
	v_add_f32_e32 v58, 1.0, v58
	v_rcp_f32_e32 v58, v58
	s_nop 0
	v_mul_f32_e32 v54, v54, v58
	v_mul_f32_e32 v54, v55, v54
	v_mul_f32_e32 v55, 0xbfb8aa3b, v56
	v_exp_f32_e32 v55, v55
	s_nop 0
	v_add_f32_e32 v55, 1.0, v55
	v_rcp_f32_e32 v55, v55
	s_nop 0
	v_mul_f32_e32 v55, v56, v55
	v_mul_f32_e32 v55, v57, v55
	v_cvt_pk_bf16_f32 v54, v54, v55
	v_mul_f32_e32 v55, 0xbfb8aa3b, v50
	v_exp_f32_e32 v55, v55
	s_nop 0
	v_add_f32_e32 v55, 1.0, v55
	v_rcp_f32_e32 v55, v55
	s_nop 0
	v_mul_f32_e32 v50, v50, v55
	v_mul_f32_e32 v50, v51, v50
	v_mul_f32_e32 v51, 0xbfb8aa3b, v52
	v_exp_f32_e32 v51, v51
	s_nop 0
	v_add_f32_e32 v51, 1.0, v51
	v_rcp_f32_e32 v51, v51
	s_nop 0
	v_mul_f32_e32 v51, v52, v51
	v_mul_f32_e32 v52, 0xbfb8aa3b, v46
	v_exp_f32_e32 v52, v52
	v_mul_f32_e32 v51, v53, v51
	v_cvt_pk_bf16_f32 v55, v50, v51
	global_store_dwordx2 v[66:67], v[54:55], off offset:128
	v_add_f32_e32 v52, 1.0, v52
	v_rcp_f32_e32 v52, v52
	v_mad_i64_i32 v[50:51], s[30:31], v158, s96, v[132:133]
	v_lshl_add_u64 v[50:51], v[50:51], 0, v[156:157]
	v_mul_f32_e32 v46, v46, v52
	v_mul_f32_e32 v46, v47, v46
	v_mul_f32_e32 v47, 0xbfb8aa3b, v48
	v_exp_f32_e32 v47, v47
	s_nop 0
	v_add_f32_e32 v47, 1.0, v47
	v_rcp_f32_e32 v47, v47
	s_nop 0
	v_mul_f32_e32 v47, v48, v47
	v_mul_f32_e32 v47, v49, v47
	v_cvt_pk_bf16_f32 v46, v46, v47
	v_mul_f32_e32 v47, 0xbfb8aa3b, v42
	v_exp_f32_e32 v47, v47
	s_nop 0
	v_add_f32_e32 v47, 1.0, v47
	v_rcp_f32_e32 v47, v47
	s_nop 0
	v_mul_f32_e32 v42, v42, v47
	v_mul_f32_e32 v42, v43, v42
	v_mul_f32_e32 v43, 0xbfb8aa3b, v44
	v_exp_f32_e32 v43, v43
	s_nop 0
	v_add_f32_e32 v43, 1.0, v43
; __device__ __forceinline__ unsigned cvt_pk_bf16(float lo, float hi) { unsigned r; asm volatile("v_cvt_pk_bf16_f32 %0, %1, %2" : "=v"(r) : "v"(lo), "v"(hi)); return r; }
;     __device__ __forceinline__ static float sg(float g, float uu) { return g * __builtin_amdgcn_rcpf(1.0f + __builtin_amdgcn_exp2f(-1.4426950408889634f * g)) * uu; }
;     __device__ __forceinline__ void operator()(const f32x4 (&acc)[2][2][4][2], const Unit& u, int wr, int wc, int fr, int fq) const {
;     ...
;         for (int ai = 0; ai < 2; ++ai)
; #pragma unroll
;             for (int m = 0; m < 4; ++m) {
;                 const int row = row0 + ai * HALF + m * 16;
;                 const float rs = rsv[ai][m];
;                 bf16_t* rowp = H + (size_t)row * ldh + (col0 >> 1);
; #pragma unroll
;                 for (int bj = 0; bj < 2; ++bj) {
;                     const f32x4 v0 = acc[ai][bj][m][0] * rs, v1 = acc[ai][bj][m][1] * rs;
;                     u32x2 w; w.x = cvt_pk_bf16(sg(v0[0], v0[1]), sg(v0[2], v0[3])); w.y = cvt_pk_bf16(sg(v1[0], v1[1]), sg(v1[2], v1[3]));
;                     *(u32x2*)(rowp + bj * (HALF / 2)) = w;
;                 }
;             }
	v_rcp_f32_e32 v43, v43
	s_nop 0
	v_mul_f32_e32 v43, v44, v43
	v_mul_f32_e32 v43, v45, v43
	v_cvt_pk_bf16_f32 v47, v42, v43
	v_mul_f32_e32 v42, 0xbfb8aa3b, v38
	v_exp_f32_e32 v42, v42
	global_store_dwordx2 v[50:51], v[46:47], off
	v_add_f32_e32 v42, 1.0, v42
	v_rcp_f32_e32 v42, v42
	s_nop 0
	v_mul_f32_e32 v38, v38, v42
	v_mul_f32_e32 v38, v39, v38
	v_mul_f32_e32 v39, 0xbfb8aa3b, v40
	v_exp_f32_e32 v39, v39
	s_nop 0
	v_add_f32_e32 v39, 1.0, v39
	v_rcp_f32_e32 v39, v39
	s_nop 0
	v_mul_f32_e32 v39, v40, v39
	v_mul_f32_e32 v39, v41, v39
	v_cvt_pk_bf16_f32 v38, v38, v39
	v_mul_f32_e32 v39, 0xbfb8aa3b, v34
	v_exp_f32_e32 v39, v39
	s_nop 0
	v_add_f32_e32 v39, 1.0, v39
	v_rcp_f32_e32 v39, v39
	s_nop 0
	v_mul_f32_e32 v34, v34, v39
	v_mul_f32_e32 v34, v35, v34
	v_mul_f32_e32 v35, 0xbfb8aa3b, v36
	v_exp_f32_e32 v35, v35
	s_nop 0
	v_add_f32_e32 v35, 1.0, v35
	v_rcp_f32_e32 v35, v35
	s_nop 0
	v_mul_f32_e32 v35, v36, v35
	v_mul_f32_e32 v36, 0xbfb8aa3b, v30
	v_exp_f32_e32 v36, v36
	v_mul_f32_e32 v35, v37, v35
	v_cvt_pk_bf16_f32 v39, v34, v35
	global_store_dwordx2 v[50:51], v[38:39], off offset:128
	v_add_f32_e32 v36, 1.0, v36
	v_rcp_f32_e32 v36, v36
	v_mad_i64_i32 v[34:35], s[30:31], v152, s96, v[132:133]
	v_lshl_add_u64 v[34:35], v[34:35], 0, v[156:157]
	v_mul_f32_e32 v30, v30, v36
	v_mul_f32_e32 v30, v31, v30
	v_mul_f32_e32 v31, 0xbfb8aa3b, v32
	v_exp_f32_e32 v31, v31
	s_nop 0
	v_add_f32_e32 v31, 1.0, v31
	v_rcp_f32_e32 v31, v31
	s_nop 0
	v_mul_f32_e32 v31, v32, v31
	v_mul_f32_e32 v31, v33, v31
	v_cvt_pk_bf16_f32 v30, v30, v31
	v_mul_f32_e32 v31, 0xbfb8aa3b, v26
	v_exp_f32_e32 v31, v31
	s_nop 0
	v_add_f32_e32 v31, 1.0, v31
	v_rcp_f32_e32 v31, v31
	s_nop 0
	v_mul_f32_e32 v26, v26, v31
	v_mul_f32_e32 v26, v27, v26
	v_mul_f32_e32 v27, 0xbfb8aa3b, v28
	v_exp_f32_e32 v27, v27
	s_nop 0
	v_add_f32_e32 v27, 1.0, v27
	v_rcp_f32_e32 v27, v27
	s_nop 0
	v_mul_f32_e32 v27, v28, v27
	v_mul_f32_e32 v27, v29, v27
	v_cvt_pk_bf16_f32 v31, v26, v27
	v_mul_f32_e32 v26, 0xbfb8aa3b, v22
	v_exp_f32_e32 v26, v26
	global_store_dwordx2 v[34:35], v[30:31], off
	v_add_f32_e32 v26, 1.0, v26
	v_rcp_f32_e32 v26, v26
	s_nop 0
	v_mul_f32_e32 v22, v22, v26
	v_mul_f32_e32 v22, v23, v22
	v_mul_f32_e32 v23, 0xbfb8aa3b, v24
	v_exp_f32_e32 v23, v23
	s_nop 0
	v_add_f32_e32 v23, 1.0, v23
	v_rcp_f32_e32 v23, v23
	s_nop 0
	v_mul_f32_e32 v23, v24, v23
	v_mul_f32_e32 v23, v25, v23
	v_cvt_pk_bf16_f32 v22, v22, v23
	v_mul_f32_e32 v23, 0xbfb8aa3b, v18
	v_exp_f32_e32 v23, v23
	s_nop 0
	v_add_f32_e32 v23, 1.0, v23
	v_rcp_f32_e32 v23, v23
	s_nop 0
	v_mul_f32_e32 v18, v18, v23
	v_mul_f32_e32 v18, v19, v18
	v_mul_f32_e32 v19, 0xbfb8aa3b, v20
	v_exp_f32_e32 v19, v19
	s_nop 0
	v_add_f32_e32 v19, 1.0, v19
	v_rcp_f32_e32 v19, v19
	s_nop 0
	v_mul_f32_e32 v19, v20, v19
	v_mul_f32_e32 v20, 0xbfb8aa3b, v14
	v_exp_f32_e32 v20, v20
	v_mul_f32_e32 v19, v21, v19
	v_cvt_pk_bf16_f32 v23, v18, v19
	global_store_dwordx2 v[34:35], v[22:23], off offset:128
	v_add_f32_e32 v20, 1.0, v20
	v_rcp_f32_e32 v20, v20
	v_mad_i64_i32 v[18:19], s[30:31], v148, s96, v[132:133]
	v_lshl_add_u64 v[18:19], v[18:19], 0, v[156:157]
	v_mul_f32_e32 v14, v14, v20
	v_mul_f32_e32 v14, v15, v14
	v_mul_f32_e32 v15, 0xbfb8aa3b, v16
	v_exp_f32_e32 v15, v15
	s_mov_b64 s[30:31], -1
	v_add_f32_e32 v15, 1.0, v15
	v_rcp_f32_e32 v15, v15
	s_nop 0
	v_mul_f32_e32 v15, v16, v15
	v_mul_f32_e32 v15, v17, v15
	v_cvt_pk_bf16_f32 v14, v14, v15
	v_mul_f32_e32 v15, 0xbfb8aa3b, v10
	v_exp_f32_e32 v15, v15
	s_nop 0
	v_add_f32_e32 v15, 1.0, v15
	v_rcp_f32_e32 v15, v15
	s_nop 0
	v_mul_f32_e32 v10, v10, v15
	v_mul_f32_e32 v10, v11, v10
	v_mul_f32_e32 v11, 0xbfb8aa3b, v12
	v_exp_f32_e32 v11, v11
	s_nop 0
	v_add_f32_e32 v11, 1.0, v11
	v_rcp_f32_e32 v11, v11
	s_nop 0
	v_mul_f32_e32 v11, v12, v11
	v_mul_f32_e32 v11, v13, v11
	v_cvt_pk_bf16_f32 v15, v10, v11
	v_mul_f32_e32 v10, 0xbfb8aa3b, v6
	v_exp_f32_e32 v10, v10
	global_store_dwordx2 v[18:19], v[14:15], off
	v_add_f32_e32 v10, 1.0, v10
	v_rcp_f32_e32 v10, v10
	s_nop 0
	v_mul_f32_e32 v6, v6, v10
	v_mul_f32_e32 v6, v7, v6
	v_mul_f32_e32 v7, 0xbfb8aa3b, v8
	v_exp_f32_e32 v7, v7
	s_nop 0
	v_add_f32_e32 v7, 1.0, v7
	v_rcp_f32_e32 v7, v7
	s_nop 0
	v_mul_f32_e32 v7, v8, v7
	v_mul_f32_e32 v7, v9, v7
	v_cvt_pk_bf16_f32 v6, v6, v7
	v_mul_f32_e32 v7, 0xbfb8aa3b, v2
	v_exp_f32_e32 v7, v7
	s_nop 0
	v_add_f32_e32 v7, 1.0, v7
	v_rcp_f32_e32 v7, v7
	s_nop 0
	v_mul_f32_e32 v2, v2, v7
	v_mul_f32_e32 v2, v3, v2
	v_mul_f32_e32 v3, 0xbfb8aa3b, v4
	v_exp_f32_e32 v3, v3
	s_nop 0
	v_add_f32_e32 v3, 1.0, v3
	v_rcp_f32_e32 v3, v3
	s_nop 0
	v_mul_f32_e32 v3, v4, v3
	v_mul_f32_e32 v3, v5, v3
	v_cvt_pk_bf16_f32 v7, v2, v3
	global_store_dwordx2 v[18:19], v[6:7], off offset:128
	s_cbranch_vccnz .LBB0_3152
	s_andn2_b64 vcc, exec, s[20:21]
	s_cbranch_vccnz .LBB0_3151
	s_barrier
	s_branch .LBB0_3151

; __device__ __forceinline__ unsigned cvt_pk_bf16(float lo, float hi) { unsigned r; asm volatile("v_cvt_pk_bf16_f32 %0, %1, %2" : "=v"(r) : "v"(lo), "v"(hi)); return r; }
;     __device__ __forceinline__ void operator()(const f32x4 (&acc)[2][2][4][2], const Unit& u, int wr, int wc, int fr, int fq) const {
;         const int row0 = u.pm * BM + wr * 64 + fr, col0 = u.pn * BM + wc * 32 + 8 * fq;
;         float rsv[2][4];
; #pragma unroll
;         for (int ai = 0; ai < 2; ++ai) {
; #pragma unroll
;             for (int m = 0; m < 4; ++m) rsv[ai][m] = ssq ? row_rstd16_coop(ssq, row0 + ai * HALF + m * 16, fq, 1.0f / 1024.0f) : 1.0f;
;         }
; #pragma unroll
;         for (int ai = 0; ai < 2; ++ai)
; #pragma unroll
;             for (int m = 0; m < 4; ++m) {
;                 const int row = row0 + ai * HALF + m * 16;
;                 const float rs = rsv[ai][m];
;                 bf16_t* rowp = O + (size_t)row * ldc + col0;
; #pragma unroll
;                 for (int bj = 0; bj < 2; ++bj) {
;                     const f32x4 v0 = acc[ai][bj][m][0] * rs, v1 = acc[ai][bj][m][1] * rs;
;                     u32x4 w; w.x = cvt_pk_bf16(v0[0], v0[1]); w.y = cvt_pk_bf16(v0[2], v0[3]); w.z = cvt_pk_bf16(v1[0], v1[1]); w.w = cvt_pk_bf16(v1[2], v1[3]);
;                     *(u32x4*)(rowp + bj * HALF) = w;
.Lmy_rs_cached_1:
	v_lshlrev_b32_e32 v210, 2, v1
	v_add_u32_e32 v210, 0x21000, v210
	ds_read_b32 v180, v210
	ds_read_b32 v184, v210 offset:64
	ds_read_b32 v188, v210 offset:128
	ds_read_b32 v192, v210 offset:192
	ds_read_b32 v196, v210 offset:512
	ds_read_b32 v200, v210 offset:576
	ds_read_b32 v204, v210 offset:640
	ds_read_b32 v208, v210 offset:704
	s_waitcnt lgkmcnt(0)
	v_lshl_add_u32 v162, s55, 8, v1
	v_ashrrev_i32_e32 v163, 31, v162
	v_lshlrev_b64 v[130:131], 6, v[162:163]
	v_lshl_add_u64 v[130:131], v[142:143], 0, v[130:131]
	v_or_b32_e32 v164, 16, v162
	v_ashrrev_i32_e32 v165, 31, v164
	v_or_b32_e32 v166, 32, v162
	v_ashrrev_i32_e32 v167, 31, v166
	v_or_b32_e32 v168, 48, v162
	v_ashrrev_i32_e32 v169, 31, v168
	v_add_u32_e32 v170, 0x80, v162
	v_ashrrev_i32_e32 v171, 31, v170
	v_add_u32_e32 v172, 0x90, v162
	v_ashrrev_i32_e32 v173, 31, v172
	v_add_u32_e32 v174, 0xa0, v162
	v_ashrrev_i32_e32 v175, 31, v174
	v_add_u32_e32 v176, 0xb0, v162
	v_ashrrev_i32_e32 v177, 31, v176
	v_mad_i64_i32 v[162:163], s[26:27], v162, s30, 0
	v_lshl_add_u64 v[162:163], v[162:163], 1, s[18:19]
	s_and_b64 vcc, exec, s[4:5]
	v_mov_b32_e32 v154, v131
	v_mov_b32_e32 v155, v132
	s_nop 0
	s_nop 1
	s_waitcnt lgkmcnt(0)
	s_nop 1
	s_waitcnt lgkmcnt(0)
	v_mov_b32_e32 v148, v180
	s_nop 1
	v_pk_mul_f32 v[128:129], v[128:129], v[148:149] op_sel_hi:[1,0]
	v_pk_mul_f32 v[126:127], v[126:127], v[148:149] op_sel_hi:[1,0]
	v_pk_mul_f32 v[120:121], v[120:121], v[148:149] op_sel_hi:[1,0]
	v_pk_mul_f32 v[118:119], v[118:119], v[148:149] op_sel_hi:[1,0]
	s_nop 0
	s_nop 1
	s_waitcnt lgkmcnt(0)
	s_nop 1
	s_waitcnt lgkmcnt(0)
	v_mov_b32_e32 v150, v184
	s_nop 1
	v_pk_mul_f32 v[112:113], v[112:113], v[150:151] op_sel_hi:[1,0]
	v_pk_mul_f32 v[110:111], v[110:111], v[150:151] op_sel_hi:[1,0]
	v_pk_mul_f32 v[104:105], v[104:105], v[150:151] op_sel_hi:[1,0]
	v_pk_mul_f32 v[102:103], v[102:103], v[150:151] op_sel_hi:[1,0]
	s_nop 0
	s_nop 1
	s_waitcnt lgkmcnt(0)
	s_nop 1
	s_waitcnt lgkmcnt(0)
	v_mov_b32_e32 v152, v188
	s_nop 1
	v_pk_mul_f32 v[96:97], v[96:97], v[152:153] op_sel_hi:[1,0]
	v_pk_mul_f32 v[94:95], v[94:95], v[152:153] op_sel_hi:[1,0]
	v_pk_mul_f32 v[88:89], v[88:89], v[152:153] op_sel_hi:[1,0]
	v_pk_mul_f32 v[86:87], v[86:87], v[152:153] op_sel_hi:[1,0]
	s_nop 0
	s_nop 1
	s_waitcnt lgkmcnt(0)
	s_nop 1
	s_waitcnt lgkmcnt(0)
	v_mov_b32_e32 v154, v192
	s_nop 1
	v_pk_mul_f32 v[80:81], v[80:81], v[154:155] op_sel_hi:[1,0]
	v_pk_mul_f32 v[78:79], v[78:79], v[154:155] op_sel_hi:[1,0]
	v_pk_mul_f32 v[72:73], v[72:73], v[154:155] op_sel_hi:[1,0]
	v_pk_mul_f32 v[70:71], v[70:71], v[154:155] op_sel_hi:[1,0]
	s_nop 0
	s_nop 1
	s_waitcnt lgkmcnt(0)
	s_nop 1
	s_waitcnt lgkmcnt(0)
	v_mov_b32_e32 v156, v196
	s_nop 1
	v_pk_mul_f32 v[64:65], v[64:65], v[156:157] op_sel_hi:[1,0]
	v_pk_mul_f32 v[62:63], v[62:63], v[156:157] op_sel_hi:[1,0]
	v_pk_mul_f32 v[56:57], v[56:57], v[156:157] op_sel_hi:[1,0]
	v_pk_mul_f32 v[54:55], v[54:55], v[156:157] op_sel_hi:[1,0]
	s_nop 0
	s_nop 1
	s_waitcnt lgkmcnt(0)
	s_nop 1
	s_waitcnt lgkmcnt(0)
	v_mov_b32_e32 v158, v200
	s_nop 1
	v_pk_mul_f32 v[48:49], v[48:49], v[158:159] op_sel_hi:[1,0]
	v_pk_mul_f32 v[46:47], v[46:47], v[158:159] op_sel_hi:[1,0]
	v_pk_mul_f32 v[40:41], v[40:41], v[158:159] op_sel_hi:[1,0]
	v_pk_mul_f32 v[38:39], v[38:39], v[158:159] op_sel_hi:[1,0]
	s_nop 0
	s_nop 1
	s_waitcnt lgkmcnt(0)
	s_nop 1
	s_waitcnt lgkmcnt(0)
	v_mov_b32_e32 v160, v204
	s_nop 1
	v_mov_b32_e32 v130, v204
	v_mov_b32_e32 v131, v205
	v_mov_b32_e32 v132, v206
	v_mov_b32_e32 v133, v207
	v_pk_mul_f32 v[32:33], v[32:33], v[160:161] op_sel_hi:[1,0]
	v_pk_mul_f32 v[30:31], v[30:31], v[160:161] op_sel_hi:[1,0]
	v_pk_mul_f32 v[24:25], v[24:25], v[160:161] op_sel_hi:[1,0]
	v_pk_mul_f32 v[22:23], v[22:23], v[160:161] op_sel_hi:[1,0]
	v_mov_b32_e32 v179, v132
	v_lshl_or_b32 v132, s54, 8, v151
	v_mov_b32_e32 v178, v131
	v_ashrrev_i32_e32 v133, 31, v132
	v_lshlrev_b64 v[132:133], 1, v[132:133]
	v_lshl_add_u64 v[162:163], v[162:163], 0, v[132:133]
	v_pk_mul_f32 v[178:179], v[124:125], v[148:149] op_sel_hi:[1,0]
	v_pk_mul_f32 v[124:125], v[122:123], v[148:149] op_sel_hi:[1,0]
	v_cvt_pk_bf16_f32 v122, v126, v127
	v_cvt_pk_bf16_f32 v123, v128, v129
	v_cvt_pk_bf16_f32 v124, v124, v125
	v_cvt_pk_bf16_f32 v125, v178, v179
	s_waitcnt vmcnt(0)
	global_store_dwordx4 v[162:163], v[122:125], off
	s_nop 1
	s_nop 1
	s_nop 1
	s_waitcnt lgkmcnt(0)
	v_pk_mul_f32 v[122:123], v[116:117], v[148:149] op_sel_hi:[1,0]
	v_pk_mul_f32 v[116:117], v[114:115], v[148:149] op_sel_hi:[1,0]
	v_cvt_pk_bf16_f32 v114, v118, v119
	v_cvt_pk_bf16_f32 v115, v120, v121
	s_nop 1
	v_cvt_pk_bf16_f32 v116, v116, v117
	v_cvt_pk_bf16_f32 v117, v122, v123
	global_store_dwordx4 v[162:163], v[114:117], off offset:256
	s_waitcnt lgkmcnt(0)
	s_nop 1
	v_mad_i64_i32 v[114:115], s[26:27], v164, s30, 0
	v_lshl_add_u64 v[114:115], v[114:115], 1, s[18:19]
	v_lshl_add_u64 v[114:115], v[114:115], 0, v[132:133]
	v_pk_mul_f32 v[116:117], v[108:109], v[150:151] op_sel_hi:[1,0]
	v_pk_mul_f32 v[108:109], v[106:107], v[150:151] op_sel_hi:[1,0]
	v_cvt_pk_bf16_f32 v106, v110, v111
	v_cvt_pk_bf16_f32 v107, v112, v113
	v_cvt_pk_bf16_f32 v108, v108, v109
	v_cvt_pk_bf16_f32 v109, v116, v117
	global_store_dwordx4 v[114:115], v[106:109], off
	v_mov_b32_e32 v130, v208

;     __device__ __forceinline__ void operator()(const f32x4 (&acc)[2][2][4][2], const Unit& u, int wr, int wc, int fr, int fq) const {
;         const int row0 = u.pm * BM + wr * 64 + fr, col0 = u.pn * BM + wc * 32 + 8 * fq;
;         float rsv[2][4];
; #pragma unroll
;         for (int ai = 0; ai < 2; ++ai) {
; #pragma unroll
;             for (int m = 0; m < 4; ++m) rsv[ai][m] = row_rstd16_coop(ssq, row0 + ai * HALF + m * 16, fq, 1.0f / 1024.0f);
;         }
; #pragma unroll
;         for (int ai = 0; ai < 2; ++ai)
; #pragma unroll
;             for (int m = 0; m < 4; ++m) {
;                 const int row = row0 + ai * HALF + m * 16;
;                 const float rs = rsv[ai][m];
;                 bf16_t* rowp = H + (size_t)row * ldh + (col0 >> 1);
; #pragma unroll
;                 for (int bj = 0; bj < 2; ++bj) {
;                     const f32x4 v0 = acc[ai][bj][m][0] * rs, v1 = acc[ai][bj][m][1] * rs;
.Lmy_rs_cached_3:
	v_lshlrev_b32_e32 v212, 2, v1
	v_add_u32_e32 v212, 0x21000, v212
	ds_read_b32 v182, v212
	ds_read_b32 v186, v212 offset:64
	ds_read_b32 v190, v212 offset:128
	ds_read_b32 v194, v212 offset:192
	ds_read_b32 v198, v212 offset:512
	ds_read_b32 v202, v212 offset:576
	ds_read_b32 v206, v212 offset:640
	ds_read_b32 v210, v212 offset:704
	s_waitcnt lgkmcnt(0)
	v_lshl_add_u32 v156, s52, 8, v1
	v_ashrrev_i32_e32 v157, 31, v156
	v_lshlrev_b64 v[130:131], 6, v[156:157]
	v_lshl_add_u64 v[130:131], v[142:143], 0, v[130:131]
	v_or_b32_e32 v174, 16, v156
	v_ashrrev_i32_e32 v175, 31, v174
	v_or_b32_e32 v170, 32, v156
	v_ashrrev_i32_e32 v171, 31, v170
	v_or_b32_e32 v166, 48, v156
	v_ashrrev_i32_e32 v167, 31, v166
	v_add_u32_e32 v162, 0x80, v156
	v_ashrrev_i32_e32 v163, 31, v162
	v_add_u32_e32 v158, 0x90, v156
	v_ashrrev_i32_e32 v159, 31, v158
	v_add_u32_e32 v152, 0xa0, v156
	v_ashrrev_i32_e32 v153, 31, v152
	s_and_b64 vcc, exec, s[4:5]
	v_mov_b32_e32 v148, v131
	v_mov_b32_e32 v149, v132
	s_nop 0
	s_nop 1
	s_waitcnt lgkmcnt(0)
	s_nop 1
	s_waitcnt lgkmcnt(0)
	v_mov_b32_e32 v176, v182
	s_nop 1
	v_pk_mul_f32 v[122:123], v[122:123], v[176:177] op_sel_hi:[1,0]
	v_pk_mul_f32 v[124:125], v[124:125], v[176:177] op_sel_hi:[1,0]
	v_pk_mul_f32 v[126:127], v[126:127], v[176:177] op_sel_hi:[1,0]
	v_pk_mul_f32 v[128:129], v[128:129], v[176:177] op_sel_hi:[1,0]
	v_pk_mul_f32 v[118:119], v[118:119], v[176:177] op_sel_hi:[1,0]
	v_pk_mul_f32 v[120:121], v[120:121], v[176:177] op_sel_hi:[1,0]
	v_pk_mul_f32 v[114:115], v[114:115], v[176:177] op_sel_hi:[1,0]
	v_pk_mul_f32 v[116:117], v[116:117], v[176:177] op_sel_hi:[1,0]
	s_nop 0
	s_nop 1
	s_waitcnt lgkmcnt(0)
	s_nop 1
	s_waitcnt lgkmcnt(0)
	v_mov_b32_e32 v172, v186
	s_nop 1
	v_pk_mul_f32 v[110:111], v[110:111], v[172:173] op_sel_hi:[1,0]
	v_pk_mul_f32 v[112:113], v[112:113], v[172:173] op_sel_hi:[1,0]
	v_pk_mul_f32 v[106:107], v[106:107], v[172:173] op_sel_hi:[1,0]
	v_pk_mul_f32 v[108:109], v[108:109], v[172:173] op_sel_hi:[1,0]
	v_pk_mul_f32 v[102:103], v[102:103], v[172:173] op_sel_hi:[1,0]
	v_pk_mul_f32 v[104:105], v[104:105], v[172:173] op_sel_hi:[1,0]
	v_pk_mul_f32 v[98:99], v[98:99], v[172:173] op_sel_hi:[1,0]
	v_pk_mul_f32 v[100:101], v[100:101], v[172:173] op_sel_hi:[1,0]
	s_nop 0
	s_nop 1
	s_waitcnt lgkmcnt(0)
	s_nop 1
	s_waitcnt lgkmcnt(0)
	v_mov_b32_e32 v168, v190
	s_nop 1
	v_pk_mul_f32 v[94:95], v[94:95], v[168:169] op_sel_hi:[1,0]
	v_pk_mul_f32 v[96:97], v[96:97], v[168:169] op_sel_hi:[1,0]
	v_pk_mul_f32 v[90:91], v[90:91], v[168:169] op_sel_hi:[1,0]
	v_pk_mul_f32 v[92:93], v[92:93], v[168:169] op_sel_hi:[1,0]
	v_pk_mul_f32 v[86:87], v[86:87], v[168:169] op_sel_hi:[1,0]
	v_pk_mul_f32 v[88:89], v[88:89], v[168:169] op_sel_hi:[1,0]
	v_pk_mul_f32 v[82:83], v[82:83], v[168:169] op_sel_hi:[1,0]
	v_pk_mul_f32 v[84:85], v[84:85], v[168:169] op_sel_hi:[1,0]
	s_nop 0
	s_nop 1
	s_waitcnt lgkmcnt(0)
	s_nop 1
	s_waitcnt lgkmcnt(0)
	v_mov_b32_e32 v164, v194
	s_nop 1
	v_pk_mul_f32 v[78:79], v[78:79], v[164:165] op_sel_hi:[1,0]
	v_pk_mul_f32 v[80:81], v[80:81], v[164:165] op_sel_hi:[1,0]
	v_pk_mul_f32 v[74:75], v[74:75], v[164:165] op_sel_hi:[1,0]
	v_pk_mul_f32 v[76:77], v[76:77], v[164:165] op_sel_hi:[1,0]
	v_pk_mul_f32 v[70:71], v[70:71], v[164:165] op_sel_hi:[1,0]
	v_pk_mul_f32 v[72:73], v[72:73], v[164:165] op_sel_hi:[1,0]
	v_pk_mul_f32 v[66:67], v[66:67], v[164:165] op_sel_hi:[1,0]
	v_pk_mul_f32 v[68:69], v[68:69], v[164:165] op_sel_hi:[1,0]
	s_nop 0
	s_nop 1
	s_waitcnt lgkmcnt(0)
	s_nop 1
	s_waitcnt lgkmcnt(0)
	v_mov_b32_e32 v160, v198
	s_nop 1
	v_pk_mul_f32 v[62:63], v[62:63], v[160:161] op_sel_hi:[1,0]
	v_pk_mul_f32 v[64:65], v[64:65], v[160:161] op_sel_hi:[1,0]
	v_pk_mul_f32 v[58:59], v[58:59], v[160:161] op_sel_hi:[1,0]
	v_pk_mul_f32 v[60:61], v[60:61], v[160:161] op_sel_hi:[1,0]
	v_pk_mul_f32 v[54:55], v[54:55], v[160:161] op_sel_hi:[1,0]
	v_pk_mul_f32 v[56:57], v[56:57], v[160:161] op_sel_hi:[1,0]
	v_pk_mul_f32 v[50:51], v[50:51], v[160:161] op_sel_hi:[1,0]
	v_pk_mul_f32 v[52:53], v[52:53], v[160:161] op_sel_hi:[1,0]
	s_nop 0
	s_nop 1
	s_waitcnt lgkmcnt(0)
	s_nop 1
	s_waitcnt lgkmcnt(0)
	v_mov_b32_e32 v154, v202
	s_nop 1
	v_pk_mul_f32 v[46:47], v[46:47], v[154:155] op_sel_hi:[1,0]
	v_pk_mul_f32 v[48:49], v[48:49], v[154:155] op_sel_hi:[1,0]
	v_pk_mul_f32 v[42:43], v[42:43], v[154:155] op_sel_hi:[1,0]
	v_pk_mul_f32 v[44:45], v[44:45], v[154:155] op_sel_hi:[1,0]
	v_pk_mul_f32 v[38:39], v[38:39], v[154:155] op_sel_hi:[1,0]
	v_pk_mul_f32 v[40:41], v[40:41], v[154:155] op_sel_hi:[1,0]
	v_pk_mul_f32 v[34:35], v[34:35], v[154:155] op_sel_hi:[1,0]
	v_pk_mul_f32 v[36:37], v[36:37], v[154:155] op_sel_hi:[1,0]
	v_add_u32_e32 v148, 0xb0, v156
	s_nop 1
	v_ashrrev_i32_e32 v149, 31, v148
	s_waitcnt lgkmcnt(0)
	s_nop 1
	s_waitcnt lgkmcnt(0)
	v_mov_b32_e32 v150, v206
	s_nop 1
	v_pk_mul_f32 v[30:31], v[30:31], v[150:151] op_sel_hi:[1,0]
	v_pk_mul_f32 v[32:33], v[32:33], v[150:151] op_sel_hi:[1,0]
	v_pk_mul_f32 v[26:27], v[26:27], v[150:151] op_sel_hi:[1,0]
	v_pk_mul_f32 v[28:29], v[28:29], v[150:151] op_sel_hi:[1,0]
	v_pk_mul_f32 v[22:23], v[22:23], v[150:151] op_sel_hi:[1,0]
	v_pk_mul_f32 v[24:25], v[24:25], v[150:151] op_sel_hi:[1,0]
	v_pk_mul_f32 v[18:19], v[18:19], v[150:151] op_sel_hi:[1,0]
	v_pk_mul_f32 v[20:21], v[20:21], v[150:151] op_sel_hi:[1,0]
	v_mov_b64_e32 v[132:133], s[16:17]
	s_nop 1
	v_mad_i64_i32 v[180:181], s[24:25], v156, s96, v[132:133]
	s_waitcnt lgkmcnt(0)
	s_nop 1
	s_waitcnt lgkmcnt(0)
	v_lshl_or_b32 v131, s51, 8, v155
	v_ashrrev_i32_e32 v178, 1, v131
	v_mul_f32_e32 v131, 0xbfb8aa3b, v122
	v_exp_f32_e32 v131, v131
	v_ashrrev_i32_e32 v179, 31, v178
	v_lshlrev_b64 v[156:157], 1, v[178:179]
	v_lshl_add_u64 v[178:179], v[180:181], 0, v[156:157]
	v_add_f32_e32 v131, 1.0, v131
	v_rcp_f32_e32 v131, v131
	v_mov_b32_e32 v130, v210
; __device__ __forceinline__ unsigned cvt_pk_bf16(float lo, float hi) { unsigned r; asm volatile("v_cvt_pk_bf16_f32 %0, %1, %2" : "=v"(r) : "v"(lo), "v"(hi)); return r; }
;     __device__ __forceinline__ static float sg(float g, float uu) { return g * __builtin_amdgcn_rcpf(1.0f + __builtin_amdgcn_exp2f(-1.4426950408889634f * g)) * uu; }
;     __device__ __forceinline__ void operator()(const f32x4 (&acc)[2][2][4][2], const Unit& u, int wr, int wc, int fr, int fq) const {
;         const int row0 = u.pm * BM + wr * 64 + fr, col0 = u.pn * BM + wc * 32 + 8 * fq;
;         float rsv[2][4];
; #pragma unroll
;         for (int ai = 0; ai < 2; ++ai) {
; #pragma unroll
;             for (int m = 0; m < 4; ++m) rsv[ai][m] = row_rstd16_coop(ssq, row0 + ai * HALF + m * 16, fq, 1.0f / 1024.0f);
;         }
; #pragma unroll
;         for (int ai = 0; ai < 2; ++ai)
; #pragma unroll
;             for (int m = 0; m < 4; ++m) {
;                 const int row = row0 + ai * HALF + m * 16;
;                 const float rs = rsv[ai][m];
;                 bf16_t* rowp = H + (size_t)row * ldh + (col0 >> 1);
; #pragma unroll
;                 for (int bj = 0; bj < 2; ++bj) {
;                     const f32x4 v0 = acc[ai][bj][m][0] * rs, v1 = acc[ai][bj][m][1] * rs;
;                     u32x2 w; w.x = cvt_pk_bf16(sg(v0[0], v0[1]), sg(v0[2], v0[3])); w.y = cvt_pk_bf16(sg(v1[0], v1[1]), sg(v1[2], v1[3]));
;                     *(u32x2*)(rowp + bj * (HALF / 2)) = w;
;                 }
;             }
.Lmy_rs_join_3:
	v_mul_f32_e32 v122, v122, v131
	v_mul_f32_e32 v122, v123, v122
	v_mul_f32_e32 v123, 0xbfb8aa3b, v124
	v_exp_f32_e32 v123, v123
	v_pk_mul_f32 v[14:15], v[14:15], v[130:131] op_sel_hi:[1,0]
	v_pk_mul_f32 v[16:17], v[16:17], v[130:131] op_sel_hi:[1,0]
	v_pk_mul_f32 v[10:11], v[10:11], v[130:131] op_sel_hi:[1,0]
	v_add_f32_e32 v123, 1.0, v123
	v_rcp_f32_e32 v123, v123
	v_pk_mul_f32 v[12:13], v[12:13], v[130:131] op_sel_hi:[1,0]
	v_pk_mul_f32 v[6:7], v[6:7], v[130:131] op_sel_hi:[1,0]
	v_pk_mul_f32 v[8:9], v[8:9], v[130:131] op_sel_hi:[1,0]
	v_mul_f32_e32 v123, v124, v123
	v_mul_f32_e32 v123, v125, v123
	v_cvt_pk_bf16_f32 v122, v122, v123
	v_mul_f32_e32 v123, 0xbfb8aa3b, v126
	v_exp_f32_e32 v123, v123
	v_mul_f32_e32 v124, 0xbfb8aa3b, v128
	v_exp_f32_e32 v124, v124
	v_pk_mul_f32 v[2:3], v[2:3], v[130:131] op_sel_hi:[1,0]
	v_add_f32_e32 v123, 1.0, v123
	v_rcp_f32_e32 v123, v123
	v_add_f32_e32 v124, 1.0, v124
	v_rcp_f32_e32 v124, v124
	v_pk_mul_f32 v[4:5], v[4:5], v[130:131] op_sel_hi:[1,0]
	v_mul_f32_e32 v123, v126, v123
	v_mul_f32_e32 v123, v127, v123
	v_mul_f32_e32 v124, v128, v124
	v_mul_f32_e32 v124, v129, v124
	v_cvt_pk_bf16_f32 v123, v123, v124
	s_waitcnt vmcnt(0)
	global_store_dwordx2 v[178:179], v[122:123], off
	v_mul_f32_e32 v122, 0xbfb8aa3b, v118
	v_exp_f32_e32 v122, v122
	s_nop 0
	v_add_f32_e32 v122, 1.0, v122
	v_rcp_f32_e32 v122, v122
	s_nop 0
	v_mul_f32_e32 v118, v118, v122
	v_mul_f32_e32 v118, v119, v118
	v_mul_f32_e32 v119, 0xbfb8aa3b, v120
	v_exp_f32_e32 v119, v119
	s_nop 0
	v_add_f32_e32 v119, 1.0, v119
	v_rcp_f32_e32 v119, v119
	s_nop 0
	v_mul_f32_e32 v119, v120, v119
	v_mul_f32_e32 v119, v121, v119
	v_cvt_pk_bf16_f32 v118, v118, v119
	v_mul_f32_e32 v119, 0xbfb8aa3b, v114
	v_exp_f32_e32 v119, v119
	s_nop 0
	v_add_f32_e32 v119, 1.0, v119
	v_rcp_f32_e32 v119, v119
	s_nop 0
	v_mul_f32_e32 v114, v114, v119
	v_mul_f32_e32 v114, v115, v114
	v_mul_f32_e32 v115, 0xbfb8aa3b, v116
	v_exp_f32_e32 v115, v115
	s_nop 0
	v_add_f32_e32 v115, 1.0, v115
	v_rcp_f32_e32 v115, v115
	s_nop 0
	v_mul_f32_e32 v115, v116, v115
	v_mul_f32_e32 v116, 0xbfb8aa3b, v110
	v_exp_f32_e32 v116, v116
	v_mul_f32_e32 v115, v117, v115
	v_cvt_pk_bf16_f32 v119, v114, v115
	global_store_dwordx2 v[178:179], v[118:119], off offset:128
	v_add_f32_e32 v116, 1.0, v116
	v_rcp_f32_e32 v116, v116
	v_mad_i64_i32 v[114:115], s[24:25], v174, s96, v[132:133]
	v_lshl_add_u64 v[114:115], v[114:115], 0, v[156:157]
	v_mul_f32_e32 v110, v110, v116
	v_mul_f32_e32 v110, v111, v110
	v_mul_f32_e32 v111, 0xbfb8aa3b, v112
	v_exp_f32_e32 v111, v111
	s_nop 0
	v_add_f32_e32 v111, 1.0, v111
	v_rcp_f32_e32 v111, v111
	s_nop 0
	v_mul_f32_e32 v111, v112, v111
	v_mul_f32_e32 v111, v113, v111
	v_cvt_pk_bf16_f32 v110, v110, v111
	v_mul_f32_e32 v111, 0xbfb8aa3b, v106
	v_exp_f32_e32 v111, v111
	s_nop 0
	v_add_f32_e32 v111, 1.0, v111
	v_rcp_f32_e32 v111, v111
	s_nop 0
	v_mul_f32_e32 v106, v106, v111
	v_mul_f32_e32 v106, v107, v106
	v_mul_f32_e32 v107, 0xbfb8aa3b, v108
	v_exp_f32_e32 v107, v107
	s_nop 0
	v_add_f32_e32 v107, 1.0, v107
	v_rcp_f32_e32 v107, v107
	s_nop 0
	v_mul_f32_e32 v107, v108, v107
	v_mul_f32_e32 v107, v109, v107
	v_cvt_pk_bf16_f32 v111, v106, v107
	v_mul_f32_e32 v106, 0xbfb8aa3b, v102
	v_exp_f32_e32 v106, v106
	global_store_dwordx2 v[114:115], v[110:111], off
	v_add_f32_e32 v106, 1.0, v106
	v_rcp_f32_e32 v106, v106
	s_nop 0
	v_mul_f32_e32 v102, v102, v106
	v_mul_f32_e32 v102, v103, v102
	v_mul_f32_e32 v103, 0xbfb8aa3b, v104
	v_exp_f32_e32 v103, v103
	s_nop 0
	v_add_f32_e32 v103, 1.0, v103
	v_rcp_f32_e32 v103, v103
	s_nop 0
	v_mul_f32_e32 v103, v104, v103
	v_mul_f32_e32 v103, v105, v103
	v_cvt_pk_bf16_f32 v102, v102, v103
	v_mul_f32_e32 v103, 0xbfb8aa3b, v98
	v_exp_f32_e32 v103, v103
	s_nop 0
	v_add_f32_e32 v103, 1.0, v103
	v_rcp_f32_e32 v103, v103
	s_nop 0
	v_mul_f32_e32 v98, v98, v103
	v_mul_f32_e32 v98, v99, v98
	v_mul_f32_e32 v99, 0xbfb8aa3b, v100
	v_exp_f32_e32 v99, v99
	s_nop 0
	v_add_f32_e32 v99, 1.0, v99
	v_rcp_f32_e32 v99, v99
	s_nop 0
	v_mul_f32_e32 v99, v100, v99
	v_mul_f32_e32 v100, 0xbfb8aa3b, v94
	v_exp_f32_e32 v100, v100
	v_mul_f32_e32 v99, v101, v99
	v_cvt_pk_bf16_f32 v103, v98, v99
	global_store_dwordx2 v[114:115], v[102:103], off offset:128
	v_add_f32_e32 v100, 1.0, v100
	v_rcp_f32_e32 v100, v100
	v_mad_i64_i32 v[98:99], s[24:25], v170, s96, v[132:133]
	v_lshl_add_u64 v[98:99], v[98:99], 0, v[156:157]
	v_mul_f32_e32 v94, v94, v100
	v_mul_f32_e32 v94, v95, v94
	v_mul_f32_e32 v95, 0xbfb8aa3b, v96
	v_exp_f32_e32 v95, v95
	s_nop 0
	v_add_f32_e32 v95, 1.0, v95
	v_rcp_f32_e32 v95, v95
	s_nop 0
	v_mul_f32_e32 v95, v96, v95
	v_mul_f32_e32 v95, v97, v95
	v_cvt_pk_bf16_f32 v94, v94, v95
	v_mul_f32_e32 v95, 0xbfb8aa3b, v90
	v_exp_f32_e32 v95, v95
	s_nop 0
	v_add_f32_e32 v95, 1.0, v95
	v_rcp_f32_e32 v95, v95
	s_nop 0
	v_mul_f32_e32 v90, v90, v95
	v_mul_f32_e32 v90, v91, v90
	v_mul_f32_e32 v91, 0xbfb8aa3b, v92
	v_exp_f32_e32 v91, v91
	s_nop 0
	v_add_f32_e32 v91, 1.0, v91
	v_rcp_f32_e32 v91, v91
	s_nop 0
	v_mul_f32_e32 v91, v92, v91
	v_mul_f32_e32 v91, v93, v91
	v_cvt_pk_bf16_f32 v95, v90, v91
	v_mul_f32_e32 v90, 0xbfb8aa3b, v86
	v_exp_f32_e32 v90, v90
	global_store_dwordx2 v[98:99], v[94:95], off
	v_add_f32_e32 v90, 1.0, v90
	v_rcp_f32_e32 v90, v90
	s_nop 0
	v_mul_f32_e32 v86, v86, v90
	v_mul_f32_e32 v86, v87, v86
	v_mul_f32_e32 v87, 0xbfb8aa3b, v88
	v_exp_f32_e32 v87, v87
	s_nop 0
	v_add_f32_e32 v87, 1.0, v87
	v_rcp_f32_e32 v87, v87
	s_nop 0
	v_mul_f32_e32 v87, v88, v87
	v_mul_f32_e32 v87, v89, v87
	v_cvt_pk_bf16_f32 v86, v86, v87
	v_mul_f32_e32 v87, 0xbfb8aa3b, v82
	v_exp_f32_e32 v87, v87
	s_nop 0
	v_add_f32_e32 v87, 1.0, v87
	v_rcp_f32_e32 v87, v87
	s_nop 0
; __device__ __forceinline__ unsigned cvt_pk_bf16(float lo, float hi) { unsigned r; asm volatile("v_cvt_pk_bf16_f32 %0, %1, %2" : "=v"(r) : "v"(lo), "v"(hi)); return r; }
;     __device__ __forceinline__ static float sg(float g, float uu) { return g * __builtin_amdgcn_rcpf(1.0f + __builtin_amdgcn_exp2f(-1.4426950408889634f * g)) * uu; }
;     __device__ __forceinline__ void operator()(const f32x4 (&acc)[2][2][4][2], const Unit& u, int wr, int wc, int fr, int fq) const {
;     ...
;         for (int ai = 0; ai < 2; ++ai)
; #pragma unroll
;             for (int m = 0; m < 4; ++m) {
;                 const int row = row0 + ai * HALF + m * 16;
;                 const float rs = rsv[ai][m];
;                 bf16_t* rowp = H + (size_t)row * ldh + (col0 >> 1);
; #pragma unroll
;                 for (int bj = 0; bj < 2; ++bj) {
;                     const f32x4 v0 = acc[ai][bj][m][0] * rs, v1 = acc[ai][bj][m][1] * rs;
;                     u32x2 w; w.x = cvt_pk_bf16(sg(v0[0], v0[1]), sg(v0[2], v0[3])); w.y = cvt_pk_bf16(sg(v1[0], v1[1]), sg(v1[2], v1[3]));
;                     *(u32x2*)(rowp + bj * (HALF / 2)) = w;
;                 }
;             }
	v_mul_f32_e32 v82, v82, v87
	v_mul_f32_e32 v82, v83, v82
	v_mul_f32_e32 v83, 0xbfb8aa3b, v84
	v_exp_f32_e32 v83, v83
	s_nop 0
	v_add_f32_e32 v83, 1.0, v83
	v_rcp_f32_e32 v83, v83
	s_nop 0
	v_mul_f32_e32 v83, v84, v83
	v_mul_f32_e32 v84, 0xbfb8aa3b, v78
	v_exp_f32_e32 v84, v84
	v_mul_f32_e32 v83, v85, v83
	v_cvt_pk_bf16_f32 v87, v82, v83
	global_store_dwordx2 v[98:99], v[86:87], off offset:128
	v_add_f32_e32 v84, 1.0, v84
	v_rcp_f32_e32 v84, v84
	v_mad_i64_i32 v[82:83], s[24:25], v166, s96, v[132:133]
	v_lshl_add_u64 v[82:83], v[82:83], 0, v[156:157]
	v_mul_f32_e32 v78, v78, v84
	v_mul_f32_e32 v78, v79, v78
	v_mul_f32_e32 v79, 0xbfb8aa3b, v80
	v_exp_f32_e32 v79, v79
	s_nop 0
	v_add_f32_e32 v79, 1.0, v79
	v_rcp_f32_e32 v79, v79
	s_nop 0
	v_mul_f32_e32 v79, v80, v79
	v_mul_f32_e32 v79, v81, v79
	v_cvt_pk_bf16_f32 v78, v78, v79
	v_mul_f32_e32 v79, 0xbfb8aa3b, v74
	v_exp_f32_e32 v79, v79
	s_nop 0
	v_add_f32_e32 v79, 1.0, v79
	v_rcp_f32_e32 v79, v79
	s_nop 0
	v_mul_f32_e32 v74, v74, v79
	v_mul_f32_e32 v74, v75, v74
	v_mul_f32_e32 v75, 0xbfb8aa3b, v76
	v_exp_f32_e32 v75, v75
	s_nop 0
	v_add_f32_e32 v75, 1.0, v75
	v_rcp_f32_e32 v75, v75
	s_nop 0
	v_mul_f32_e32 v75, v76, v75
	v_mul_f32_e32 v75, v77, v75
	v_cvt_pk_bf16_f32 v79, v74, v75
	v_mul_f32_e32 v74, 0xbfb8aa3b, v70
	v_exp_f32_e32 v74, v74
	global_store_dwordx2 v[82:83], v[78:79], off
	v_add_f32_e32 v74, 1.0, v74
	v_rcp_f32_e32 v74, v74
	s_nop 0
	v_mul_f32_e32 v70, v70, v74
	v_mul_f32_e32 v70, v71, v70
	v_mul_f32_e32 v71, 0xbfb8aa3b, v72
	v_exp_f32_e32 v71, v71
	s_nop 0
	v_add_f32_e32 v71, 1.0, v71
	v_rcp_f32_e32 v71, v71
	s_nop 0
	v_mul_f32_e32 v71, v72, v71
	v_mul_f32_e32 v71, v73, v71
	v_cvt_pk_bf16_f32 v70, v70, v71
	v_mul_f32_e32 v71, 0xbfb8aa3b, v66
	v_exp_f32_e32 v71, v71
	s_nop 0
	v_add_f32_e32 v71, 1.0, v71
	v_rcp_f32_e32 v71, v71
	s_nop 0
	v_mul_f32_e32 v66, v66, v71
	v_mul_f32_e32 v66, v67, v66
	v_mul_f32_e32 v67, 0xbfb8aa3b, v68
	v_exp_f32_e32 v67, v67
	s_nop 0
	v_add_f32_e32 v67, 1.0, v67
	v_rcp_f32_e32 v67, v67
	s_nop 0
	v_mul_f32_e32 v67, v68, v67
	v_mul_f32_e32 v68, 0xbfb8aa3b, v62
	v_exp_f32_e32 v68, v68
	v_mul_f32_e32 v67, v69, v67
	v_cvt_pk_bf16_f32 v71, v66, v67
	global_store_dwordx2 v[82:83], v[70:71], off offset:128
	v_add_f32_e32 v68, 1.0, v68
	v_rcp_f32_e32 v68, v68
	v_mad_i64_i32 v[66:67], s[24:25], v162, s96, v[132:133]
	v_lshl_add_u64 v[66:67], v[66:67], 0, v[156:157]
	v_mul_f32_e32 v62, v62, v68
	v_mul_f32_e32 v62, v63, v62
	v_mul_f32_e32 v63, 0xbfb8aa3b, v64
	v_exp_f32_e32 v63, v63
	s_nop 0
	v_add_f32_e32 v63, 1.0, v63
	v_rcp_f32_e32 v63, v63
	s_nop 0
	v_mul_f32_e32 v63, v64, v63
	v_mul_f32_e32 v63, v65, v63
	v_cvt_pk_bf16_f32 v62, v62, v63
	v_mul_f32_e32 v63, 0xbfb8aa3b, v58
	v_exp_f32_e32 v63, v63
	s_nop 0
	v_add_f32_e32 v63, 1.0, v63
	v_rcp_f32_e32 v63, v63
	s_nop 0
	v_mul_f32_e32 v58, v58, v63
	v_mul_f32_e32 v58, v59, v58
	v_mul_f32_e32 v59, 0xbfb8aa3b, v60
	v_exp_f32_e32 v59, v59
	s_nop 0
	v_add_f32_e32 v59, 1.0, v59
	v_rcp_f32_e32 v59, v59
	s_nop 0
	v_mul_f32_e32 v59, v60, v59
	v_mul_f32_e32 v59, v61, v59
	v_cvt_pk_bf16_f32 v63, v58, v59
	v_mul_f32_e32 v58, 0xbfb8aa3b, v54
	v_exp_f32_e32 v58, v58
	global_store_dwordx2 v[66:67], v[62:63], off
	v_add_f32_e32 v58, 1.0, v58
	v_rcp_f32_e32 v58, v58
	s_nop 0
	v_mul_f32_e32 v54, v54, v58
	v_mul_f32_e32 v54, v55, v54
	v_mul_f32_e32 v55, 0xbfb8aa3b, v56
	v_exp_f32_e32 v55, v55
	s_nop 0
	v_add_f32_e32 v55, 1.0, v55
	v_rcp_f32_e32 v55, v55
	s_nop 0
	v_mul_f32_e32 v55, v56, v55
	v_mul_f32_e32 v55, v57, v55
	v_cvt_pk_bf16_f32 v54, v54, v55
	v_mul_f32_e32 v55, 0xbfb8aa3b, v50
	v_exp_f32_e32 v55, v55
	s_nop 0
	v_add_f32_e32 v55, 1.0, v55
	v_rcp_f32_e32 v55, v55
	s_nop 0
	v_mul_f32_e32 v50, v50, v55
	v_mul_f32_e32 v50, v51, v50
	v_mul_f32_e32 v51, 0xbfb8aa3b, v52
	v_exp_f32_e32 v51, v51
	s_nop 0
	v_add_f32_e32 v51, 1.0, v51
	v_rcp_f32_e32 v51, v51
	s_nop 0
	v_mul_f32_e32 v51, v52, v51
	v_mul_f32_e32 v52, 0xbfb8aa3b, v46
	v_exp_f32_e32 v52, v52
	v_mul_f32_e32 v51, v53, v51
	v_cvt_pk_bf16_f32 v55, v50, v51
	global_store_dwordx2 v[66:67], v[54:55], off offset:128
	v_add_f32_e32 v52, 1.0, v52
	v_rcp_f32_e32 v52, v52
	v_mad_i64_i32 v[50:51], s[24:25], v158, s96, v[132:133]
	v_lshl_add_u64 v[50:51], v[50:51], 0, v[156:157]
	v_mul_f32_e32 v46, v46, v52
	v_mul_f32_e32 v46, v47, v46
	v_mul_f32_e32 v47, 0xbfb8aa3b, v48
	v_exp_f32_e32 v47, v47
	s_nop 0
	v_add_f32_e32 v47, 1.0, v47
	v_rcp_f32_e32 v47, v47
	s_nop 0
	v_mul_f32_e32 v47, v48, v47
	v_mul_f32_e32 v47, v49, v47
	v_cvt_pk_bf16_f32 v46, v46, v47
	v_mul_f32_e32 v47, 0xbfb8aa3b, v42
	v_exp_f32_e32 v47, v47
	s_nop 0
	v_add_f32_e32 v47, 1.0, v47
	v_rcp_f32_e32 v47, v47
	s_nop 0
	v_mul_f32_e32 v42, v42, v47
	v_mul_f32_e32 v42, v43, v42
	v_mul_f32_e32 v43, 0xbfb8aa3b, v44
	v_exp_f32_e32 v43, v43
	s_nop 0
	v_add_f32_e32 v43, 1.0, v43
; __device__ __forceinline__ unsigned cvt_pk_bf16(float lo, float hi) { unsigned r; asm volatile("v_cvt_pk_bf16_f32 %0, %1, %2" : "=v"(r) : "v"(lo), "v"(hi)); return r; }
;     __device__ __forceinline__ static float sg(float g, float uu) { return g * __builtin_amdgcn_rcpf(1.0f + __builtin_amdgcn_exp2f(-1.4426950408889634f * g)) * uu; }
;     __device__ __forceinline__ void operator()(const f32x4 (&acc)[2][2][4][2], const Unit& u, int wr, int wc, int fr, int fq) const {
;     ...
;         for (int ai = 0; ai < 2; ++ai)
; #pragma unroll
;             for (int m = 0; m < 4; ++m) {
;                 const int row = row0 + ai * HALF + m * 16;
;                 const float rs = rsv[ai][m];
;                 bf16_t* rowp = H + (size_t)row * ldh + (col0 >> 1);
; #pragma unroll
;                 for (int bj = 0; bj < 2; ++bj) {
;                     const f32x4 v0 = acc[ai][bj][m][0] * rs, v1 = acc[ai][bj][m][1] * rs;
;                     u32x2 w; w.x = cvt_pk_bf16(sg(v0[0], v0[1]), sg(v0[2], v0[3])); w.y = cvt_pk_bf16(sg(v1[0], v1[1]), sg(v1[2], v1[3]));
;                     *(u32x2*)(rowp + bj * (HALF / 2)) = w;
;                 }
;             }
	v_rcp_f32_e32 v43, v43
	s_nop 0
	v_mul_f32_e32 v43, v44, v43
	v_mul_f32_e32 v43, v45, v43
	v_cvt_pk_bf16_f32 v47, v42, v43
	v_mul_f32_e32 v42, 0xbfb8aa3b, v38
	v_exp_f32_e32 v42, v42
	global_store_dwordx2 v[50:51], v[46:47], off
	v_add_f32_e32 v42, 1.0, v42
	v_rcp_f32_e32 v42, v42
	s_nop 0
	v_mul_f32_e32 v38, v38, v42
	v_mul_f32_e32 v38, v39, v38
	v_mul_f32_e32 v39, 0xbfb8aa3b, v40
	v_exp_f32_e32 v39, v39
	s_nop 0
	v_add_f32_e32 v39, 1.0, v39
	v_rcp_f32_e32 v39, v39
	s_nop 0
	v_mul_f32_e32 v39, v40, v39
	v_mul_f32_e32 v39, v41, v39
	v_cvt_pk_bf16_f32 v38, v38, v39
	v_mul_f32_e32 v39, 0xbfb8aa3b, v34
	v_exp_f32_e32 v39, v39
	s_nop 0
	v_add_f32_e32 v39, 1.0, v39
	v_rcp_f32_e32 v39, v39
	s_nop 0
	v_mul_f32_e32 v34, v34, v39
	v_mul_f32_e32 v34, v35, v34
	v_mul_f32_e32 v35, 0xbfb8aa3b, v36
	v_exp_f32_e32 v35, v35
	s_nop 0
	v_add_f32_e32 v35, 1.0, v35
	v_rcp_f32_e32 v35, v35
	s_nop 0
	v_mul_f32_e32 v35, v36, v35
	v_mul_f32_e32 v36, 0xbfb8aa3b, v30
	v_exp_f32_e32 v36, v36
	v_mul_f32_e32 v35, v37, v35
	v_cvt_pk_bf16_f32 v39, v34, v35
	global_store_dwordx2 v[50:51], v[38:39], off offset:128
	v_add_f32_e32 v36, 1.0, v36
	v_rcp_f32_e32 v36, v36
	v_mad_i64_i32 v[34:35], s[24:25], v152, s96, v[132:133]
	v_lshl_add_u64 v[34:35], v[34:35], 0, v[156:157]
	v_mul_f32_e32 v30, v30, v36
	v_mul_f32_e32 v30, v31, v30
	v_mul_f32_e32 v31, 0xbfb8aa3b, v32
	v_exp_f32_e32 v31, v31
	s_nop 0
	v_add_f32_e32 v31, 1.0, v31
	v_rcp_f32_e32 v31, v31
	s_nop 0
	v_mul_f32_e32 v31, v32, v31
	v_mul_f32_e32 v31, v33, v31
	v_cvt_pk_bf16_f32 v30, v30, v31
	v_mul_f32_e32 v31, 0xbfb8aa3b, v26
	v_exp_f32_e32 v31, v31
	s_nop 0
	v_add_f32_e32 v31, 1.0, v31
	v_rcp_f32_e32 v31, v31
	s_nop 0
	v_mul_f32_e32 v26, v26, v31
	v_mul_f32_e32 v26, v27, v26
	v_mul_f32_e32 v27, 0xbfb8aa3b, v28
	v_exp_f32_e32 v27, v27
	s_nop 0
	v_add_f32_e32 v27, 1.0, v27
	v_rcp_f32_e32 v27, v27
	s_nop 0
	v_mul_f32_e32 v27, v28, v27
	v_mul_f32_e32 v27, v29, v27
	v_cvt_pk_bf16_f32 v31, v26, v27
	v_mul_f32_e32 v26, 0xbfb8aa3b, v22
	v_exp_f32_e32 v26, v26
	global_store_dwordx2 v[34:35], v[30:31], off
	v_add_f32_e32 v26, 1.0, v26
	v_rcp_f32_e32 v26, v26
	s_nop 0
	v_mul_f32_e32 v22, v22, v26
	v_mul_f32_e32 v22, v23, v22
	v_mul_f32_e32 v23, 0xbfb8aa3b, v24
	v_exp_f32_e32 v23, v23
	s_nop 0
	v_add_f32_e32 v23, 1.0, v23
	v_rcp_f32_e32 v23, v23
	s_nop 0
	v_mul_f32_e32 v23, v24, v23
	v_mul_f32_e32 v23, v25, v23
	v_cvt_pk_bf16_f32 v22, v22, v23
	v_mul_f32_e32 v23, 0xbfb8aa3b, v18
	v_exp_f32_e32 v23, v23
	s_nop 0
	v_add_f32_e32 v23, 1.0, v23
	v_rcp_f32_e32 v23, v23
	s_nop 0
	v_mul_f32_e32 v18, v18, v23
	v_mul_f32_e32 v18, v19, v18
	v_mul_f32_e32 v19, 0xbfb8aa3b, v20
	v_exp_f32_e32 v19, v19
	s_nop 0
	v_add_f32_e32 v19, 1.0, v19
	v_rcp_f32_e32 v19, v19
	s_nop 0
	v_mul_f32_e32 v19, v20, v19
	v_mul_f32_e32 v20, 0xbfb8aa3b, v14
	v_exp_f32_e32 v20, v20
	v_mul_f32_e32 v19, v21, v19
	v_cvt_pk_bf16_f32 v23, v18, v19
	global_store_dwordx2 v[34:35], v[22:23], off offset:128
	v_add_f32_e32 v20, 1.0, v20
	v_rcp_f32_e32 v20, v20
	v_mad_i64_i32 v[18:19], s[24:25], v148, s96, v[132:133]
	v_lshl_add_u64 v[18:19], v[18:19], 0, v[156:157]
	v_mul_f32_e32 v14, v14, v20
	v_mul_f32_e32 v14, v15, v14
	v_mul_f32_e32 v15, 0xbfb8aa3b, v16
	v_exp_f32_e32 v15, v15
	s_mov_b64 s[24:25], -1
	v_add_f32_e32 v15, 1.0, v15
	v_rcp_f32_e32 v15, v15
	s_nop 0
	v_mul_f32_e32 v15, v16, v15
	v_mul_f32_e32 v15, v17, v15
	v_cvt_pk_bf16_f32 v14, v14, v15
	v_mul_f32_e32 v15, 0xbfb8aa3b, v10
	v_exp_f32_e32 v15, v15
	s_nop 0
	v_add_f32_e32 v15, 1.0, v15
	v_rcp_f32_e32 v15, v15
	s_nop 0
	v_mul_f32_e32 v10, v10, v15
	v_mul_f32_e32 v10, v11, v10
	v_mul_f32_e32 v11, 0xbfb8aa3b, v12
	v_exp_f32_e32 v11, v11
	s_nop 0
	v_add_f32_e32 v11, 1.0, v11
	v_rcp_f32_e32 v11, v11
	s_nop 0
	v_mul_f32_e32 v11, v12, v11
	v_mul_f32_e32 v11, v13, v11
	v_cvt_pk_bf16_f32 v15, v10, v11
	v_mul_f32_e32 v10, 0xbfb8aa3b, v6
	v_exp_f32_e32 v10, v10
	global_store_dwordx2 v[18:19], v[14:15], off
	v_add_f32_e32 v10, 1.0, v10
	v_rcp_f32_e32 v10, v10
	s_nop 0
	v_mul_f32_e32 v6, v6, v10
	v_mul_f32_e32 v6, v7, v6
	v_mul_f32_e32 v7, 0xbfb8aa3b, v8
	v_exp_f32_e32 v7, v7
	s_nop 0
	v_add_f32_e32 v7, 1.0, v7
	v_rcp_f32_e32 v7, v7
	s_nop 0
	v_mul_f32_e32 v7, v8, v7
	v_mul_f32_e32 v7, v9, v7
	v_cvt_pk_bf16_f32 v6, v6, v7
	v_mul_f32_e32 v7, 0xbfb8aa3b, v2
	v_exp_f32_e32 v7, v7
	s_nop 0
	v_add_f32_e32 v7, 1.0, v7
	v_rcp_f32_e32 v7, v7
	s_nop 0
	v_mul_f32_e32 v2, v2, v7
	v_mul_f32_e32 v2, v3, v2
	v_mul_f32_e32 v3, 0xbfb8aa3b, v4
	v_exp_f32_e32 v3, v3
	s_nop 0
	v_add_f32_e32 v3, 1.0, v3
	v_rcp_f32_e32 v3, v3
	s_nop 0
	v_mul_f32_e32 v3, v4, v3
	v_mul_f32_e32 v3, v5, v3
	v_cvt_pk_bf16_f32 v7, v2, v3
	global_store_dwordx2 v[18:19], v[6:7], off offset:128
	s_cbranch_vccnz .LBB0_4832
	s_andn2_b64 vcc, exec, s[14:15]
	s_cbranch_vccnz .LBB0_4831
	s_barrier
	s_branch .LBB0_4831
